# LN reductions via DPP+readlane, LN mode-1 LDS reads batched; scan: conflict-free 288-B pitch for KET/QK tiles, last chunk through the scheduled loop
# speedup vs baseline: 1.0293x; 1.0054x over previous
; DI void scan_phase(LAS unsigned char* lds, const Args& a, int l) {
;     ...
;     const int tid = tid_, s = tid >> 6, lane = tid & 63, fr = lane & 15, fq = lane >> 4;
;     constexpr int BUF = 62464, O_WK = 0, O_QD = 17408, O_KET = 34816, O_QK = 53248;
;     const int lw0 = (tid >> 4) * 272 + (tid & 15) * 16, lw1 = ((tid + 512) >> 4) * 272 + (tid & 15) * 16;
;     const int lk0 = (tid >> 3) * 144 + (tid & 7) * 16, lk1 = ((tid + 512) >> 3) * 144 + (tid & 7) * 16;
;     ...
;         float* dp = a.out + OUT_DP + (size_t)((l * 8 + b) * 4 + h) * 16384 + (size_t)(4 * fq) * 128 + 16 * s + fr;
; #pragma unroll
;         for (int mt = 0; mt < 8; ++mt)
; #pragma unroll
;             for (int reg = 0; reg < 4; ++reg) __builtin_nontemporal_store(S[mt][reg], dp + (size_t)(16 * mt + reg) * 128);
.LBB0_100:
	s_cmp_gt_i32 s5, 2
	s_mov_b64 s[8:9], -1
	s_cbranch_scc0 .LBB0_738
	s_cmp_lt_i32 s5, 4
	s_cbranch_scc1 .LBB0_487
	s_cmp_gt_i32 s5, 4
	s_cbranch_scc0 .LBB0_219
	v_readlane_b32 s8, v253, 54
	v_readlane_b32 s9, v253, 55
	s_andn2_b64 vcc, exec, s[8:9]
	s_cbranch_vccnz .LBB0_112
	v_readlane_b32 s8, v253, 52
	v_readlane_b32 s9, v253, 53
	s_waitcnt vmcnt(0)
	v_mov_b32_e32 v0, v152
	s_andn2_b64 vcc, exec, s[8:9]
	s_cbranch_vccnz .LBB0_112
	v_lshlrev_b32_e32 v108, 4, v0
	v_lshrrev_b32_e32 v1, 4, v0
	v_and_b32_e32 v2, 0xf0, v108
	v_mad_u64_u32 v[110:111], s[8:9], v1, s47, v[2:3]
	v_add_u32_e32 v1, 0x200, v0
	v_lshrrev_b32_e32 v3, 4, v1
	v_mad_u64_u32 v[112:113], s[8:9], v3, s47, v[2:3]
	v_lshrrev_b32_e32 v3, 3, v0
	v_and_b32_e32 v2, 0x70, v108
	s_movk_i32 s2, 0x120
	v_lshrrev_b32_e32 v1, 3, v1
	v_mad_u64_u32 v[114:115], s[8:9], v3, s2, v[2:3]
	v_mad_u64_u32 v[116:117], s[8:9], v1, s2, v[2:3]
	v_add_u32_e32 v116, 0x90, v114
	v_lshrrev_b32_e32 v151, 8, v0
	v_mul_u32_u24_e32 v151, 0x2370, v151
	v_sub_u32_e32 v151, v114, v151
	v_readlane_b32 s8, v253, 56
	v_ashrrev_i32_e32 v109, 31, v108
	v_readlane_b32 s9, v253, 57
	v_ashrrev_i32_e32 v1, 6, v0
	v_lshlrev_b32_e32 v2, 10, v1
	v_lshl_add_u64 v[118:119], s[8:9], 0, v[108:109]
	v_readlane_b32 s8, v253, 58
	v_readlane_b32 s9, v253, 59
	v_and_b32_e32 v4, 48, v0
	v_readlane_b32 s2, v254, 59
	v_lshl_add_u64 v[120:121], s[8:9], 0, v[108:109]
	v_readlane_b32 s8, v253, 60
	v_readlane_b32 s9, v253, 61
	v_ashrrev_i32_e32 v3, 31, v2
	v_add_u32_e32 v12, s2, v4
	v_lshl_add_u64 v[122:123], s[8:9], 0, v[108:109]
	v_readlane_b32 s8, v253, 62
	v_readlane_b32 s9, v253, 63
	v_readlane_b32 s2, v254, 60
	v_and_b32_e32 v6, 15, v0
	v_lshl_add_u64 v[124:125], s[8:9], 0, v[108:109]
	v_readlane_b32 s8, v254, 0
	v_and_b32_e32 v7, 63, v0
	v_bfe_u32 v8, v0, 4, 2
	v_lshlrev_b32_e32 v0, 4, v1
	v_mov_b32_e32 v5, 0x1100
	v_add_u32_e32 v13, s2, v4
	v_readlane_b32 s2, v254, 61
	v_lshlrev_b64 v[2:3], 2, v[2:3]
	v_readlane_b32 s9, v254, 1
	v_ashrrev_i32_e32 v1, 31, v0
	v_add_u32_e32 v113, 0, v4
	v_mad_u32_u24 v9, v6, s47, v5
	v_add_u32_e32 v14, s2, v4
	v_lshl_add_u64 v[4:5], s[8:9], 0, v[2:3]
	v_readlane_b32 s8, v253, 50
	v_lshlrev_b32_e32 v128, 4, v7
	v_lshlrev_b64 v[0:1], 2, v[0:1]
	v_readlane_b32 s9, v253, 51
	v_mul_u32_u24_e32 v115, 0x110, v6
	v_mad_u32_u24 v10, v6, s47, v252
	v_mad_u32_u24 v11, v6, s47, v161
	v_mul_u32_u24_e32 v117, 0x120, v6
	v_lshl_add_u64 v[126:127], v[4:5], 0, v[128:129]
	v_lshl_add_u64 v[4:5], s[8:9], 0, v[0:1]
	v_lshlrev_b32_e32 v6, 2, v6
	v_mov_b32_e32 v7, v129
	v_readlane_b32 s8, v254, 4
	v_lshl_add_u64 v[132:133], v[4:5], 0, v[6:7]
	v_lshlrev_b32_e32 v4, 11, v8
	v_mov_b32_e32 v5, v129
	v_readlane_b32 s9, v254, 5
	v_or_b32_e32 v2, v2, v128
	v_lshlrev_b32_e32 v111, 2, v8
	v_lshl_add_u64 v[4:5], s[8:9], 0, v[4:5]
	s_mov_b64 s[8:9], 0x1ece6000
	v_lshl_add_u64 v[0:1], v[4:5], 0, v[0:1]
	v_lshl_add_u64 v[136:137], v[108:109], 0, s[8:9]
	s_mov_b64 s[8:9], 0x19cea800
	s_lshl_b32 s14, s25, 5
	v_lshl_add_u64 v[134:135], v[0:1], 0, v[6:7]
	v_lshl_add_u64 v[138:139], v[2:3], 0, s[8:9]
	v_add_u32_e32 v131, v113, v9
	v_add_u32_e32 v178, v113, v11
	v_add_u32_e32 v179, v12, v115
	v_add_u32_e32 v180, v13, v117
	v_add_u32_e32 v181, v14, v117
	v_readlane_b32 s15, v254, 50
	s_mov_b32 s8, s4
	s_branch .LBB0_107
.LBB0_106:
	s_and_b32 s2, s8, -4
	s_add_i32 s2, s2, s14
	s_or_b32 s10, s2, s16
	s_ashr_i32 s11, s10, 31
	s_lshl_b64 s[10:11], s[10:11], 16
	s_movk_i32 s2, 0x6000
	s_add_i32 s8, s8, s24
	v_lshl_add_u64 v[32:33], v[134:135], 0, s[10:11]
	global_store_dword v[32:33], v0, off nt
	global_store_dword v[32:33], v1, off offset:512 nt
	global_store_dword v[32:33], v2, off offset:1024 nt
	global_store_dword v[32:33], v3, off offset:1536 nt
	v_add_co_u32_e32 v0, vcc, s93, v32
	s_nop 1
	v_addc_co_u32_e32 v1, vcc, 0, v33, vcc
	global_store_dword v[0:1], v4, off nt
	global_store_dword v[0:1], v5, off offset:512 nt
	global_store_dword v[0:1], v6, off offset:1024 nt
	global_store_dword v[0:1], v7, off offset:1536 nt
	v_add_co_u32_e32 v0, vcc, s45, v32
	s_nop 1
	v_addc_co_u32_e32 v1, vcc, 0, v33, vcc
	global_store_dword v[0:1], v8, off nt
	global_store_dword v[0:1], v9, off offset:512 nt
	global_store_dword v[0:1], v10, off offset:1024 nt
	global_store_dword v[0:1], v11, off offset:1536 nt
	v_add_co_u32_e32 v0, vcc, s2, v32
	s_mov_b32 s2, 0xa000
	s_nop 0
	v_addc_co_u32_e32 v1, vcc, 0, v33, vcc
	global_store_dword v[0:1], v12, off nt
	global_store_dword v[0:1], v13, off offset:512 nt
	global_store_dword v[0:1], v14, off offset:1024 nt
	global_store_dword v[0:1], v15, off offset:1536 nt
	v_add_co_u32_e32 v0, vcc, s49, v32
	s_nop 1
	v_addc_co_u32_e32 v1, vcc, 0, v33, vcc
	global_store_dword v[0:1], v16, off nt
	global_store_dword v[0:1], v17, off offset:512 nt
	global_store_dword v[0:1], v18, off offset:1024 nt
	global_store_dword v[0:1], v19, off offset:1536 nt
	v_add_co_u32_e32 v0, vcc, s2, v32
	s_mov_b32 s2, 0xc000
	s_nop 0
	v_addc_co_u32_e32 v1, vcc, 0, v33, vcc
	global_store_dword v[0:1], v20, off nt
	global_store_dword v[0:1], v21, off offset:512 nt
	global_store_dword v[0:1], v22, off offset:1024 nt
	global_store_dword v[0:1], v23, off offset:1536 nt
	v_add_co_u32_e32 v0, vcc, s2, v32
	v_readlane_b32 s2, v254, 51
	s_nop 0
	v_addc_co_u32_e32 v1, vcc, 0, v33, vcc
	global_store_dword v[0:1], v24, off nt
	global_store_dword v[0:1], v25, off offset:512 nt
	global_store_dword v[0:1], v26, off offset:1024 nt
	global_store_dword v[0:1], v27, off offset:1536 nt
	v_add_co_u32_e32 v0, vcc, 0xe000, v32
	s_add_i32 s15, s15, s2
	s_nop 0
	v_addc_co_u32_e32 v1, vcc, 0, v33, vcc
	s_cmp_gt_i32 s8, 31
	global_store_dword v[0:1], v28, off nt
	global_store_dword v[0:1], v29, off offset:512 nt
	global_store_dword v[0:1], v30, off offset:1024 nt
	global_store_dword v[0:1], v31, off offset:1536 nt
	s_cbranch_scc1 .LBB0_112
; #define SC_LOADUV(it_) do { const float* _u = (const float*)(a.ws + WS_UV) + (size_t)(it_) * 8192 + s * 1024 + lane * 4; \
;         uvn[0] = *(const f32x4*)_u; uvn[1] = *(const f32x4*)(_u + 256); uvn[2] = *(const f32x4*)(_u + 512); uvn[3] = *(const f32x4*)(_u + 768); \
;         gen = ((const float*)(a.ws + WS_GE))[(it_)]; } while (0)
; #define SC_STORE(bo_) do { LAS unsigned char* _b = lds + (bo_); \
;         *(LAS u32x4*)(_b + O_WK + lw0) = pf[0]; *(LAS u32x4*)(_b + O_WK + lw1) = pf[1]; *(LAS u32x4*)(_b + O_QD + lw0) = pf[2]; *(LAS u32x4*)(_b + O_QD + lw1) = pf[3]; \
;         *(LAS u32x4*)(_b + O_KET + lk0) = pf[4]; *(LAS u32x4*)(_b + O_KET + lk1) = pf[5]; *(LAS u32x4*)(_b + O_QK + lk0) = pf[6]; } while (0)
; DI void scan_phase(LAS unsigned char* lds, const Args& a, int l) {
;     ...
;     for (int bh = blockIdx.x; bh < 32; bh += gridDim.x) {
;         const int b = bh >> 2, h = bh & 3;
;         const size_t item0 = (size_t)bh * 32;
;         f32x4 S[8]; bf16x8 Sb[4];
; #pragma unroll
;         for (int i = 0; i < 8; ++i) S[i] = (f32x4){0.f, 0.f, 0.f, 0.f};
; #pragma unroll
;         for (int i = 0; i < 4; ++i) Sb[i] = (bf16x8){0, 0, 0, 0, 0, 0, 0, 0};
;         u32x4 pf[7]; f32x4 uvn[4], uvc[4]; float gen, gec;
;         SC_LOADG(item0); SC_LOADUV(item0);
;         SC_STORE(0);
; #pragma unroll
;         for (int m = 0; m < 4; ++m) uvc[m] = uvn[m];
;         gec = gen;
;         SC_LOADG(item0 + 1);
;         __syncthreads();
;         float* O = (float*)(a.ws + WS_O);
;         for (int n = 0; n < 32; ++n) {
;             const int cur = (n & 1) * BUF;
;             if (n + 1 < 32) { SC_STORE(BUF - cur); SC_LOADUV(item0 + n + 1); }
;             if (n + 2 < 32) SC_LOADG(item0 + n + 2);
.LBB0_107:
	s_ashr_i32 s9, s8, 31
	s_lshl_b64 s[12:13], s[8:9], 19
	v_lshl_add_u64 v[0:1], v[118:119], 0, s[12:13]
	v_add_co_u32_e32 v10, vcc, s93, v0
	s_lshl_b64 s[10:11], s[8:9], 18
	v_lshl_add_u64 v[8:9], v[120:121], 0, s[12:13]
	v_addc_co_u32_e32 v11, vcc, 0, v1, vcc
	s_and_b32 s2, s15, 0xfffff800
	s_lshl_b64 s[34:35], s[8:9], 7
	v_add_co_u32_e32 v18, vcc, s93, v8
	s_add_u32 s17, s34, 0x1f4e2004
	v_lshl_add_u64 v[16:17], v[122:123], 0, s[12:13]
	v_addc_co_u32_e32 v19, vcc, 0, v9, vcc
	s_addc_u32 s28, s35, 0
	s_lshl_b64 s[36:37], s[8:9], 20
	s_and_b32 s16, s8, 3
	s_lshl_b64 s[38:39], s[8:9], 5
	v_readlane_b32 s40, v254, 2
	v_add_co_u32_e32 v20, vcc, s93, v16
	v_readlane_b32 s41, v254, 3
	s_add_u32 s34, s40, s34
	v_addc_co_u32_e32 v21, vcc, 0, v17, vcc
	v_lshl_add_u64 v[24:25], v[124:125], 0, s[10:11]
	v_lshl_add_u64 v[28:29], v[126:127], 0, s[36:37]
	s_addc_u32 s35, s41, s35
	s_or_b32 s38, s38, 1
	global_load_dwordx4 v[0:3], v[0:1], off
	s_nop 0
	global_load_dwordx4 v[4:7], v[8:9], off
	s_nop 0
	global_load_dwordx4 v[8:11], v[10:11], off
	s_nop 0
	global_load_dwordx4 v[12:15], v[16:17], off
	s_nop 0
	global_load_dwordx4 v[16:19], v[18:19], off
	s_nop 0
	global_load_dwordx4 v[20:23], v[20:21], off
	v_or_b32_e32 v142, s2, v111
	global_load_dwordx4 v[24:27], v[24:25], off
	s_nop 0
	global_load_dwordx4 v[104:107], v[28:29], off
	global_load_dwordx4 v[96:99], v[28:29], off offset:1024
	global_load_dwordx4 v[92:95], v[28:29], off offset:2048
	global_load_dword v150, v129, s[34:35]
	s_lshl_b64 s[34:35], s[38:39], 14
	v_lshl_add_u64 v[30:31], v[118:119], 0, s[34:35]
	global_load_dwordx4 v[100:103], v[28:29], off offset:3072
	global_load_dwordx4 v[48:51], v[30:31], off
	v_add_co_u32_e32 v28, vcc, s93, v30
	v_lshl_add_u64 v[32:33], v[120:121], 0, s[34:35]
	s_nop 0
	v_addc_co_u32_e32 v29, vcc, 0, v31, vcc
	v_add_co_u32_e32 v30, vcc, s93, v32
	v_lshl_add_u64 v[34:35], v[122:123], 0, s[34:35]
	s_nop 0
	v_addc_co_u32_e32 v31, vcc, 0, v33, vcc
	global_load_dwordx4 v[52:55], v[28:29], off
	global_load_dwordx4 v[60:63], v[30:31], off
	global_load_dwordx4 v[56:59], v[32:33], off
	global_load_dwordx4 v[64:67], v[34:35], off
	v_add_co_u32_e32 v28, vcc, s93, v34
	s_lshl_b64 s[34:35], s[38:39], 13
	s_nop 0
	v_addc_co_u32_e32 v29, vcc, 0, v35, vcc
	v_lshl_add_u64 v[30:31], v[124:125], 0, s[34:35]
	global_load_dwordx4 v[68:71], v[28:29], off
	global_load_dwordx4 v[72:75], v[30:31], off
	v_add_u32_e32 v28, 0, v110
	v_add_u32_e32 v29, 0, v112
	v_add_u32_e32 v30, 0, v114
	v_add_u32_e32 v31, 0, v116
	s_lshl_b32 s2, s16, 9
	s_mov_b32 s9, 0
	v_lshl_add_u64 v[144:145], v[136:137], 0, s[10:11]
	v_lshl_add_u64 v[146:147], v[108:109], 0, s[12:13]
	v_lshl_add_u64 v[148:149], v[138:139], 0, s[36:37]
	v_lshl_add_u64 v[140:141], v[132:133], 0, s[2:3]
	v_mov_b32_e32 v76, 0
	v_mov_b32_e32 v77, 0
	v_mov_b32_e32 v78, 0
	v_mov_b32_e32 v79, 0
	v_mov_b32_e32 v80, 0
	v_mov_b32_e32 v81, 0
	v_mov_b32_e32 v82, 0
	v_mov_b32_e32 v83, 0
	v_mov_b32_e32 v84, 0
	v_mov_b32_e32 v85, 0
	v_mov_b32_e32 v86, 0
	v_mov_b32_e32 v87, 0
	v_mov_b32_e32 v88, 0
	v_mov_b32_e32 v89, 0
	v_mov_b32_e32 v90, 0
	v_mov_b32_e32 v91, 0
	s_waitcnt vmcnt(18)
	ds_write_b128 v28, v[0:3]
	s_waitcnt vmcnt(16)
	ds_write_b128 v29, v[8:11]
	ds_write_b128 v28, v[4:7] offset:17408
	s_waitcnt vmcnt(14)
	ds_write_b128 v29, v[16:19] offset:17408
	ds_write_b128 v30, v[12:15] offset:34816
	s_waitcnt vmcnt(13)
	ds_write_b128 v31, v[20:23] offset:34816
	s_waitcnt vmcnt(12)
	ds_write_b128 v151, v[24:27] offset:53248
	v_mov_b32_e32 v0, 0
	v_mov_b32_e32 v1, v0
	v_mov_b32_e32 v2, v0
	v_mov_b32_e32 v3, v0
	v_mov_b32_e32 v4, v0
	v_mov_b32_e32 v5, v0
	v_mov_b32_e32 v6, v0
	v_mov_b32_e32 v7, v0
	v_mov_b32_e32 v8, v0
	v_mov_b32_e32 v9, v0
	v_mov_b32_e32 v10, v0
	v_mov_b32_e32 v11, v0
	v_mov_b32_e32 v12, v0
	v_mov_b32_e32 v13, v0
	v_mov_b32_e32 v14, v0
	v_mov_b32_e32 v15, v0
	v_mov_b32_e32 v16, v0
	v_mov_b32_e32 v17, v0
	v_mov_b32_e32 v18, v0
	v_mov_b32_e32 v19, v0
	v_mov_b32_e32 v20, v0
	v_mov_b32_e32 v21, v0
	v_mov_b32_e32 v22, v0
	v_mov_b32_e32 v23, v0
	v_mov_b32_e32 v24, v0
	v_mov_b32_e32 v25, v0
	v_mov_b32_e32 v26, v0
	v_mov_b32_e32 v27, v0
	v_mov_b32_e32 v28, v0
	v_mov_b32_e32 v29, v0
	v_mov_b32_e32 v30, v0
	v_mov_b32_e32 v31, v0
	s_waitcnt vmcnt(0) lgkmcnt(0)
	s_barrier
.LBB0_108:
	s_bitcmp1_b32 s9, 0
	s_cselect_b32 s2, 0xf400, 0
	v_add3_u32 v250, s2, v113, v115
	v_add3_u32 v251, s2, v113, v117
	s_cmp_eq_u32 s9, 31
	s_cbranch_scc1 .Lscan_nostage
	s_sub_i32 s10, 0, s2
	v_add_u32_e32 v32, s10, v110
	s_add_i32 s11, s10, 0xf400
	ds_write_b128 v32, v[48:51] offset:62464
	v_add_u32_e32 v33, s10, v112
	ds_write_b128 v33, v[52:55] offset:62464
	v_add_u32_e32 v32, s11, v110
	ds_write_b128 v32, v[56:59] offset:17408
	v_add_u32_e32 v33, s11, v112
	ds_write_b128 v33, v[60:63] offset:17408
	v_add_u32_e32 v32, s11, v114
	v_add_u32_e32 v33, s11, v116
	ds_write_b128 v32, v[64:67] offset:34816
	ds_write_b128 v33, v[68:71] offset:34816
	v_add_u32_e32 v32, s11, v151
	ds_write_b128 v32, v[72:75] offset:53248
; #define LAS __attribute__((address_space(3)))
; DI bf16x8 pack8(const f32x4& a, const f32x4& b) { u32x4 p; p.x = pk2(a[0], a[1]); p.y = pk2(a[2], a[3]); p.z = pk2(b[0], b[1]); p.w = pk2(b[2], b[3]); return __builtin_bit_cast(bf16x8, p); }
; #define MFMA16(a, b, c) __builtin_amdgcn_mfma_f32_16x16x32_bf16((a), (b), (c), 0, 0, 0)
; #define SC_LOADUV(it_) do { const float* _u = (const float*)(a.ws + WS_UV) + (size_t)(it_) * 8192 + s * 1024 + lane * 4; \
;         uvn[0] = *(const f32x4*)_u; uvn[1] = *(const f32x4*)(_u + 256); uvn[2] = *(const f32x4*)(_u + 512); uvn[3] = *(const f32x4*)(_u + 768); \
;         gen = ((const float*)(a.ws + WS_GE))[(it_)]; } while (0)
; DI void scan_phase(LAS unsigned char* lds, const Args& a, int l) {
;     ...
;             if (n + 1 < 32) { SC_STORE(BUF - cur); SC_LOADUV(item0 + n + 1); }
;             if (n + 2 < 32) SC_LOADG(item0 + n + 2);
;             const LAS unsigned char* B = lds + cur;
;             f32x4 ws[4], o[4];
; #pragma unroll
;             for (int m = 0; m < 4; ++m) { ws[m] = (f32x4){0.f, 0.f, 0.f, 0.f}; o[m] = (f32x4){0.f, 0.f, 0.f, 0.f}; }
; #pragma unroll
;             for (int ks = 0; ks < 4; ++ks)
; #pragma unroll
;                 for (int m = 0; m < 4; ++m) { const bf16x8 av = *(const LAS bf16x8*)(B + O_WK + (16 * m + fr) * 272 + (32 * ks + 8 * fq) * 2); ws[m] = MFMA16(av, Sb[ks], ws[m]); }
; #pragma unroll
;             for (int ks = 0; ks < 4; ++ks)
; #pragma unroll
;                 for (int m = 0; m < 4; ++m) { const bf16x8 av = *(const LAS bf16x8*)(B + O_QD + (16 * m + fr) * 272 + (32 * ks + 8 * fq) * 2); o[m] = MFMA16(av, Sb[ks], o[m]); }
;             f32x4 u[4];
; #pragma unroll
;             for (int m = 0; m < 4; ++m) u[m] = uvc[m] - ws[m];
;             bf16x8 Ub[2]; Ub[0] = pack8(u[0], u[1]); Ub[1] = pack8(u[2], u[3]);
; #pragma unroll
;             for (int ks = 0; ks < 2; ++ks)
; #pragma unroll
;                 for (int m = 0; m < 4; ++m) { const bf16x8 av = *(const LAS bf16x8*)(B + O_QK + (16 * m + fr) * 144 + (32 * ks + 8 * fq) * 2); o[m] = MFMA16(av, Ub[ks], o[m]); }
; #pragma unroll
;             for (int mt = 0; mt < 8; ++mt) S[mt] = S[mt] * gec;
.Lscan_nostage:
	ds_read_b128 v[214:217], v250
	ds_read_b128 v[218:221], v250 offset:4352
	ds_read_b128 v[222:225], v250 offset:8704
	ds_read_b128 v[226:229], v250 offset:13056
	ds_read_b128 v[230:233], v250 offset:64
	ds_read_b128 v[234:237], v250 offset:4416
	ds_read_b128 v[238:241], v250 offset:8768
	s_cmp_eq_u32 s9, 31
	s_cbranch_scc1 .LBB0_110
	v_lshl_add_u64 v[32:33], s[22:23], 0, v[148:149]
	global_load_dwordx4 v[44:47], v[32:33], off offset:-2048
	global_load_dwordx4 v[40:43], v[32:33], off offset:-1024
	global_load_dwordx4 v[36:39], v[32:33], off
	s_nop 0
	global_load_dwordx4 v[32:35], v[32:33], off offset:1024
	s_add_u32 s10, s22, s17
	s_addc_u32 s11, s23, s28
	global_load_dword v128, v129, s[10:11]
	s_cmp_gt_u32 s9, 29
	s_cbranch_scc1 .LBB0_110
	v_lshl_add_u64 v[64:65], s[22:23], 0, v[146:147]
	v_add_co_u32_e32 v48, vcc, 0x1bcea000, v64
	v_lshl_add_u64 v[72:73], s[22:23], 0, v[144:145]
	s_nop 0
	v_addc_co_u32_e32 v49, vcc, 0, v65, vcc
	v_add_co_u32_e32 v52, vcc, 0x1bcec000, v64
	s_nop 1
	v_addc_co_u32_e32 v53, vcc, 0, v65, vcc
	v_add_co_u32_e32 v56, vcc, 0x1ccea000, v64
	global_load_dwordx4 v[48:51], v[48:49], off
	s_nop 0
	global_load_dwordx4 v[52:55], v[52:53], off
	v_addc_co_u32_e32 v57, vcc, 0, v65, vcc
	v_add_co_u32_e32 v60, vcc, 0x1ccec000, v64
	s_nop 1
	v_addc_co_u32_e32 v61, vcc, 0, v65, vcc
	v_add_co_u32_e32 v66, vcc, 0x1dcea000, v64
	global_load_dwordx4 v[56:59], v[56:57], off
	s_nop 0
	global_load_dwordx4 v[60:63], v[60:61], off
	v_addc_co_u32_e32 v67, vcc, 0, v65, vcc
	v_add_co_u32_e32 v68, vcc, 0x1dcec000, v64
	s_nop 1
	v_addc_co_u32_e32 v69, vcc, 0, v65, vcc
	global_load_dwordx4 v[64:67], v[66:67], off
	s_nop 0
	global_load_dwordx4 v[68:71], v[68:69], off
	s_nop 0
	global_load_dwordx4 v[72:75], v[72:73], off
.LBB0_110:
	ds_read_b128 v[242:245], v250 offset:13120
	s_waitcnt lgkmcnt(7)
	v_mfma_f32_16x16x32_bf16 v[182:185], v[214:217], v[88:91], 0
	v_pk_mul_f32 v[0:1], v[150:151], v[0:1] op_sel_hi:[0,1]
	ds_read_b128 v[214:217], v250 offset:128
	s_waitcnt lgkmcnt(7)
	v_mfma_f32_16x16x32_bf16 v[186:189], v[218:221], v[88:91], 0
	v_pk_mul_f32 v[2:3], v[150:151], v[2:3] op_sel_hi:[0,1]
	s_mov_b64 s[10:11], 0x4000
	v_lshl_add_u64 v[146:147], v[146:147], 0, s[10:11]
	ds_read_b128 v[218:221], v250 offset:4480
	s_waitcnt lgkmcnt(7)
	v_mfma_f32_16x16x32_bf16 v[190:193], v[222:225], v[88:91], 0
	v_pk_mul_f32 v[4:5], v[150:151], v[4:5] op_sel_hi:[0,1]
	ds_read_b128 v[222:225], v250 offset:8832
	s_waitcnt lgkmcnt(7)
	v_mfma_f32_16x16x32_bf16 v[194:197], v[226:229], v[88:91], 0
	v_pk_mul_f32 v[6:7], v[150:151], v[6:7] op_sel_hi:[0,1]
	s_add_u32 s17, s17, 4
	s_addc_u32 s28, s28, 0
	ds_read_b128 v[226:229], v250 offset:13184
	s_waitcnt lgkmcnt(7)
	v_mfma_f32_16x16x32_bf16 v[182:185], v[230:233], v[84:87], v[182:185]
	v_pk_mul_f32 v[8:9], v[150:151], v[8:9] op_sel_hi:[0,1]
	ds_read_b128 v[230:233], v250 offset:192
	s_waitcnt lgkmcnt(7)
	v_mfma_f32_16x16x32_bf16 v[186:189], v[234:237], v[84:87], v[186:189]
	v_pk_mul_f32 v[10:11], v[150:151], v[10:11] op_sel_hi:[0,1]
	v_lshl_add_u64 v[144:145], v[144:145], 0, s[26:27]
	ds_read_b128 v[234:237], v250 offset:4544
	s_waitcnt lgkmcnt(7)
	v_mfma_f32_16x16x32_bf16 v[190:193], v[238:241], v[84:87], v[190:193]
	v_pk_mul_f32 v[12:13], v[150:151], v[12:13] op_sel_hi:[0,1]
	ds_read_b128 v[238:241], v250 offset:8896
	s_waitcnt lgkmcnt(7)
	v_mfma_f32_16x16x32_bf16 v[194:197], v[242:245], v[84:87], v[194:197]
	v_pk_mul_f32 v[14:15], v[150:151], v[14:15] op_sel_hi:[0,1]
	s_mov_b64 s[10:11], 0x8000
	v_lshl_add_u64 v[148:149], v[148:149], 0, s[10:11]
	ds_read_b128 v[242:245], v250 offset:13248
	s_waitcnt lgkmcnt(7)
	v_mfma_f32_16x16x32_bf16 v[182:185], v[214:217], v[80:83], v[182:185]
	v_pk_mul_f32 v[16:17], v[150:151], v[16:17] op_sel_hi:[0,1]
	ds_read_b128 v[214:217], v250 offset:17408
	s_waitcnt lgkmcnt(7)
	v_mfma_f32_16x16x32_bf16 v[186:189], v[218:221], v[80:83], v[186:189]
	v_pk_mul_f32 v[18:19], v[150:151], v[18:19] op_sel_hi:[0,1]
	ds_read_b128 v[218:221], v250 offset:21760
	s_waitcnt lgkmcnt(7)
	v_mfma_f32_16x16x32_bf16 v[190:193], v[222:225], v[80:83], v[190:193]
	v_pk_mul_f32 v[20:21], v[150:151], v[20:21] op_sel_hi:[0,1]
	ds_read_b128 v[222:225], v250 offset:26112
	s_waitcnt lgkmcnt(7)
	v_mfma_f32_16x16x32_bf16 v[194:197], v[226:229], v[80:83], v[194:197]
	v_pk_mul_f32 v[22:23], v[150:151], v[22:23] op_sel_hi:[0,1]
	ds_read_b128 v[226:229], v250 offset:30464
	s_waitcnt lgkmcnt(7)
	v_mfma_f32_16x16x32_bf16 v[182:185], v[230:233], v[76:79], v[182:185]
	v_pk_mul_f32 v[24:25], v[150:151], v[24:25] op_sel_hi:[0,1]
	ds_read_b128 v[230:233], v250 offset:17472
	s_waitcnt lgkmcnt(7)
	v_mfma_f32_16x16x32_bf16 v[186:189], v[234:237], v[76:79], v[186:189]
	v_pk_mul_f32 v[26:27], v[150:151], v[26:27] op_sel_hi:[0,1]
	ds_read_b128 v[234:237], v250 offset:21824
	s_waitcnt lgkmcnt(7)
	v_mfma_f32_16x16x32_bf16 v[190:193], v[238:241], v[76:79], v[190:193]
	v_pk_mul_f32 v[28:29], v[150:151], v[28:29] op_sel_hi:[0,1]
	ds_read_b128 v[238:241], v250 offset:26176
	s_waitcnt lgkmcnt(7)
	v_mfma_f32_16x16x32_bf16 v[194:197], v[242:245], v[76:79], v[194:197]
	v_pk_mul_f32 v[30:31], v[150:151], v[30:31] op_sel_hi:[0,1]
	ds_read_b128 v[242:245], v250 offset:30528
	s_waitcnt lgkmcnt(7)
	v_mfma_f32_16x16x32_bf16 v[198:201], v[214:217], v[88:91], 0
	ds_read_b128 v[214:217], v250 offset:17536
	s_waitcnt lgkmcnt(7)
	v_mfma_f32_16x16x32_bf16 v[202:205], v[218:221], v[88:91], 0
	v_sub_f32_e32 v182, v104, v182
	v_sub_f32_e32 v183, v105, v183
	v_sub_f32_e32 v184, v106, v184
	v_sub_f32_e32 v185, v107, v185
	ds_read_b128 v[218:221], v250 offset:21888
	s_waitcnt lgkmcnt(7)
; #define LAS __attribute__((address_space(3)))
; DI bf16x8 pack8(const f32x4& a, const f32x4& b) { u32x4 p; p.x = pk2(a[0], a[1]); p.y = pk2(a[2], a[3]); p.z = pk2(b[0], b[1]); p.w = pk2(b[2], b[3]); return __builtin_bit_cast(bf16x8, p); }
; #define MFMA16(a, b, c) __builtin_amdgcn_mfma_f32_16x16x32_bf16((a), (b), (c), 0, 0, 0)
; DI void scan_phase(LAS unsigned char* lds, const Args& a, int l) {
;     ...
;             for (int ks = 0; ks < 4; ++ks)
; #pragma unroll
;                 for (int m = 0; m < 4; ++m) { const bf16x8 av = *(const LAS bf16x8*)(B + O_QD + (16 * m + fr) * 272 + (32 * ks + 8 * fq) * 2); o[m] = MFMA16(av, Sb[ks], o[m]); }
;             f32x4 u[4];
; #pragma unroll
;             for (int m = 0; m < 4; ++m) u[m] = uvc[m] - ws[m];
;             bf16x8 Ub[2]; Ub[0] = pack8(u[0], u[1]); Ub[1] = pack8(u[2], u[3]);
; #pragma unroll
;             for (int ks = 0; ks < 2; ++ks)
; #pragma unroll
;                 for (int m = 0; m < 4; ++m) { const bf16x8 av = *(const LAS bf16x8*)(B + O_QK + (16 * m + fr) * 144 + (32 * ks + 8 * fq) * 2); o[m] = MFMA16(av, Ub[ks], o[m]); }
; #pragma unroll
;             for (int mt = 0; mt < 8; ++mt) S[mt] = S[mt] * gec;
; #pragma unroll
;             for (int ks = 0; ks < 2; ++ks)
; #pragma unroll
;                 for (int mt = 0; mt < 8; ++mt) { const bf16x8 av = *(const LAS bf16x8*)(B + O_KET + (16 * mt + fr) * 144 + (32 * ks + 8 * fq) * 2); S[mt] = MFMA16(av, Ub[ks], S[mt]); }
	v_mfma_f32_16x16x32_bf16 v[206:209], v[222:225], v[88:91], 0
	v_sub_f32_e32 v186, v96, v186
	v_sub_f32_e32 v187, v97, v187
	v_sub_f32_e32 v188, v98, v188
	v_sub_f32_e32 v189, v99, v189
	ds_read_b128 v[222:225], v250 offset:26240
	s_waitcnt lgkmcnt(7)
	v_mfma_f32_16x16x32_bf16 v[210:213], v[226:229], v[88:91], 0
	v_sub_f32_e32 v190, v92, v190
	v_sub_f32_e32 v191, v93, v191
	v_sub_f32_e32 v192, v94, v192
	v_sub_f32_e32 v193, v95, v193
	ds_read_b128 v[226:229], v250 offset:30592
	s_waitcnt lgkmcnt(7)
	v_mfma_f32_16x16x32_bf16 v[198:201], v[230:233], v[84:87], v[198:201]
	v_sub_f32_e32 v194, v100, v194
	v_sub_f32_e32 v195, v101, v195
	v_sub_f32_e32 v196, v102, v196
	v_sub_f32_e32 v197, v103, v197
	ds_read_b128 v[230:233], v250 offset:17600
	s_waitcnt lgkmcnt(7)
	v_mfma_f32_16x16x32_bf16 v[202:205], v[234:237], v[84:87], v[202:205]
	v_cvt_pk_bf16_f32 v246, v182, v183
	v_cvt_pk_bf16_f32 v247, v184, v185
	ds_read_b128 v[234:237], v250 offset:21952
	s_waitcnt lgkmcnt(7)
	v_mfma_f32_16x16x32_bf16 v[206:209], v[238:241], v[84:87], v[206:209]
	v_cvt_pk_bf16_f32 v248, v186, v187
	v_cvt_pk_bf16_f32 v249, v188, v189
	ds_read_b128 v[238:241], v250 offset:26304
	s_waitcnt lgkmcnt(7)
	v_mfma_f32_16x16x32_bf16 v[210:213], v[242:245], v[84:87], v[210:213]
	v_cvt_pk_bf16_f32 v182, v190, v191
	v_cvt_pk_bf16_f32 v183, v192, v193
	ds_read_b128 v[242:245], v250 offset:30656
	s_waitcnt lgkmcnt(7)
	v_mfma_f32_16x16x32_bf16 v[198:201], v[214:217], v[80:83], v[198:201]
	v_cvt_pk_bf16_f32 v184, v194, v195
	v_cvt_pk_bf16_f32 v185, v196, v197
	ds_read_b128 v[214:217], v251 offset:34816
	s_waitcnt lgkmcnt(7)
	v_mfma_f32_16x16x32_bf16 v[202:205], v[218:221], v[80:83], v[202:205]
	ds_read_b128 v[218:221], v251 offset:39424
	s_waitcnt lgkmcnt(7)
	v_mfma_f32_16x16x32_bf16 v[206:209], v[222:225], v[80:83], v[206:209]
	ds_read_b128 v[222:225], v251 offset:44032
	s_waitcnt lgkmcnt(7)
	v_mfma_f32_16x16x32_bf16 v[210:213], v[226:229], v[80:83], v[210:213]
	ds_read_b128 v[226:229], v251 offset:48640
	s_waitcnt lgkmcnt(7)
	v_mfma_f32_16x16x32_bf16 v[198:201], v[230:233], v[76:79], v[198:201]
	ds_read_b128 v[230:233], v251 offset:34960
	s_waitcnt lgkmcnt(7)
	v_mfma_f32_16x16x32_bf16 v[202:205], v[234:237], v[76:79], v[202:205]
	ds_read_b128 v[234:237], v251 offset:39568
	s_waitcnt lgkmcnt(7)
	v_mfma_f32_16x16x32_bf16 v[206:209], v[238:241], v[76:79], v[206:209]
	ds_read_b128 v[238:241], v251 offset:44176
	s_waitcnt lgkmcnt(7)
	v_mfma_f32_16x16x32_bf16 v[210:213], v[242:245], v[76:79], v[210:213]
	ds_read_b128 v[242:245], v251 offset:48784
	s_waitcnt lgkmcnt(7)
	v_mfma_f32_16x16x32_bf16 v[0:3], v[214:217], v[246:249], v[0:3]
	ds_read_b128 v[214:217], v251 offset:34880
	s_waitcnt lgkmcnt(7)
	v_mfma_f32_16x16x32_bf16 v[4:7], v[218:221], v[246:249], v[4:7]
	ds_read_b128 v[218:221], v251 offset:39488
	s_waitcnt lgkmcnt(7)
	v_mfma_f32_16x16x32_bf16 v[8:11], v[222:225], v[246:249], v[8:11]
	v_ashrrev_i32_e32 v143, 31, v142
	ds_read_b128 v[222:225], v251 offset:44096
	s_waitcnt lgkmcnt(7)
	v_mfma_f32_16x16x32_bf16 v[12:15], v[226:229], v[246:249], v[12:15]
	ds_read_b128 v[226:229], v251 offset:48704
	s_waitcnt lgkmcnt(7)
	v_mfma_f32_16x16x32_bf16 v[16:19], v[230:233], v[246:249], v[16:19]
	v_lshlrev_b64 v[162:163], 11, v[142:143]
	ds_read_b128 v[230:233], v251 offset:35024
	s_waitcnt lgkmcnt(7)
	v_mfma_f32_16x16x32_bf16 v[20:23], v[234:237], v[246:249], v[20:23]
	ds_read_b128 v[234:237], v251 offset:39632
	s_waitcnt lgkmcnt(7)
	v_mfma_f32_16x16x32_bf16 v[24:27], v[238:241], v[246:249], v[24:27]
	v_lshl_add_u64 v[162:163], v[140:141], 0, v[162:163]
	ds_read_b128 v[238:241], v251 offset:44240
	s_waitcnt lgkmcnt(7)
	v_mfma_f32_16x16x32_bf16 v[28:31], v[242:245], v[246:249], v[28:31]
	ds_read_b128 v[242:245], v251 offset:48848
	s_waitcnt lgkmcnt(7)
	v_mfma_f32_16x16x32_bf16 v[0:3], v[214:217], v[182:185], v[0:3]
	v_add_u32_e32 v142, 64, v142
	ds_read_b128 v[214:217], v251 offset:53248
	s_waitcnt lgkmcnt(7)
; #define LAS __attribute__((address_space(3)))
; DI bf16x8 pack8(const f32x4& a, const f32x4& b) { u32x4 p; p.x = pk2(a[0], a[1]); p.y = pk2(a[2], a[3]); p.z = pk2(b[0], b[1]); p.w = pk2(b[2], b[3]); return __builtin_bit_cast(bf16x8, p); }
; #define MFMA16(a, b, c) __builtin_amdgcn_mfma_f32_16x16x32_bf16((a), (b), (c), 0, 0, 0)
; DI void scan_phase(LAS unsigned char* lds, const Args& a, int l) {
;     ...
;                 for (int m = 0; m < 4; ++m) { const bf16x8 av = *(const LAS bf16x8*)(B + O_QK + (16 * m + fr) * 144 + (32 * ks + 8 * fq) * 2); o[m] = MFMA16(av, Ub[ks], o[m]); }
; #pragma unroll
;             for (int mt = 0; mt < 8; ++mt) S[mt] = S[mt] * gec;
; #pragma unroll
;             for (int ks = 0; ks < 2; ++ks)
; #pragma unroll
;                 for (int mt = 0; mt < 8; ++mt) { const bf16x8 av = *(const LAS bf16x8*)(B + O_KET + (16 * mt + fr) * 144 + (32 * ks + 8 * fq) * 2); S[mt] = MFMA16(av, Ub[ks], S[mt]); }
; #pragma unroll
;             for (int ks = 0; ks < 4; ++ks) Sb[ks] = pack8(S[2 * ks], S[2 * ks + 1]);
;             float* op = O + (size_t)(b * 2048 + n * 64 + 4 * fq) * 512 + h * 128 + 16 * s + fr;
; #pragma unroll
;             for (int m = 0; m < 4; ++m)
; #pragma unroll
;                 for (int reg = 0; reg < 4; ++reg) op[(size_t)(16 * m + reg) * 512] = o[m][reg];
; #pragma unroll
;             for (int m = 0; m < 4; ++m) uvc[m] = uvn[m];
;             gec = gen;
;             __syncthreads();
	v_mfma_f32_16x16x32_bf16 v[4:7], v[218:221], v[182:185], v[4:7]
	ds_read_b128 v[218:221], v251 offset:57856
	s_waitcnt lgkmcnt(7)
	v_mfma_f32_16x16x32_bf16 v[8:11], v[222:225], v[182:185], v[8:11]
	ds_read_b128 v[222:225], v251 offset:53392
	s_waitcnt lgkmcnt(7)
	v_mfma_f32_16x16x32_bf16 v[12:15], v[226:229], v[182:185], v[12:15]
	ds_read_b128 v[226:229], v251 offset:58000
	s_waitcnt lgkmcnt(7)
	v_mfma_f32_16x16x32_bf16 v[16:19], v[230:233], v[182:185], v[16:19]
	ds_read_b128 v[230:233], v251 offset:53312
	s_waitcnt lgkmcnt(7)
	v_mfma_f32_16x16x32_bf16 v[20:23], v[234:237], v[182:185], v[20:23]
	v_cvt_pk_bf16_f32 v88, v0, v1
	v_cvt_pk_bf16_f32 v89, v2, v3
	v_cvt_pk_bf16_f32 v90, v4, v5
	v_cvt_pk_bf16_f32 v91, v6, v7
	ds_read_b128 v[234:237], v251 offset:57920
	s_waitcnt lgkmcnt(7)
	v_mfma_f32_16x16x32_bf16 v[24:27], v[238:241], v[182:185], v[24:27]
	ds_read_b128 v[238:241], v251 offset:53456
	s_waitcnt lgkmcnt(7)
	v_mfma_f32_16x16x32_bf16 v[28:31], v[242:245], v[182:185], v[28:31]
	v_cvt_pk_bf16_f32 v84, v8, v9
	v_cvt_pk_bf16_f32 v85, v10, v11
	v_cvt_pk_bf16_f32 v86, v12, v13
	v_cvt_pk_bf16_f32 v87, v14, v15
	ds_read_b128 v[242:245], v251 offset:58064
	s_waitcnt lgkmcnt(7)
	v_mfma_f32_16x16x32_bf16 v[198:201], v[214:217], v[246:249], v[198:201]
	s_waitcnt lgkmcnt(6)
	v_mfma_f32_16x16x32_bf16 v[202:205], v[218:221], v[246:249], v[202:205]
	s_waitcnt lgkmcnt(5)
	v_mfma_f32_16x16x32_bf16 v[206:209], v[222:225], v[246:249], v[206:209]
	v_cvt_pk_bf16_f32 v80, v16, v17
	v_cvt_pk_bf16_f32 v81, v18, v19
	v_cvt_pk_bf16_f32 v82, v20, v21
	v_cvt_pk_bf16_f32 v83, v22, v23
	s_waitcnt lgkmcnt(4)
	v_mfma_f32_16x16x32_bf16 v[210:213], v[226:229], v[246:249], v[210:213]
	s_waitcnt lgkmcnt(3)
	v_mfma_f32_16x16x32_bf16 v[198:201], v[230:233], v[182:185], v[198:201]
	s_waitcnt lgkmcnt(2)
	v_mfma_f32_16x16x32_bf16 v[202:205], v[234:237], v[182:185], v[202:205]
	v_cvt_pk_bf16_f32 v76, v24, v25
	v_cvt_pk_bf16_f32 v77, v26, v27
	v_cvt_pk_bf16_f32 v78, v28, v29
	v_cvt_pk_bf16_f32 v79, v30, v31
	s_waitcnt lgkmcnt(1)
	v_mfma_f32_16x16x32_bf16 v[206:209], v[238:241], v[182:185], v[206:209]
	s_waitcnt lgkmcnt(0)
	v_mfma_f32_16x16x32_bf16 v[210:213], v[242:245], v[182:185], v[210:213]
	s_mov_b64 s[10:11], 0x1000
	v_lshl_add_u64 v[214:215], v[162:163], 0, s[10:11]
	s_mov_b64 s[10:11], 0x9000
	v_lshl_add_u64 v[216:217], v[162:163], 0, s[10:11]
	s_mov_b64 s[10:11], 0x11000
	v_lshl_add_u64 v[218:219], v[162:163], 0, s[10:11]
	s_mov_b64 s[10:11], 0x19000
	v_lshl_add_u64 v[220:221], v[162:163], 0, s[10:11]
	s_add_i32 s9, s9, 1
	global_store_dword v[214:215], v198, off offset:-4096
	global_store_dword v[214:215], v199, off offset:-2048
	global_store_dword v[214:215], v200, off
	global_store_dword v[214:215], v201, off offset:2048
	global_store_dword v[216:217], v202, off offset:-4096
	global_store_dword v[216:217], v203, off offset:-2048
	global_store_dword v[216:217], v204, off
	global_store_dword v[216:217], v205, off offset:2048
	global_store_dword v[218:219], v206, off offset:-4096
	global_store_dword v[218:219], v207, off offset:-2048
	global_store_dword v[218:219], v208, off
	global_store_dword v[218:219], v209, off offset:2048
	global_store_dword v[220:221], v210, off offset:-4096
	global_store_dword v[220:221], v211, off offset:-2048
	global_store_dword v[220:221], v212, off
	global_store_dword v[220:221], v213, off offset:2048
	s_cmp_eq_u32 s9, 32
	s_barrier
	s_cbranch_scc1 .LBB0_106
	s_waitcnt vmcnt(16)
	v_mov_b64_e32 v[102:103], v[34:35]
	v_mov_b64_e32 v[94:95], v[38:39]
	v_mov_b64_e32 v[98:99], v[42:43]
	v_mov_b64_e32 v[106:107], v[46:47]
	v_mov_b64_e32 v[100:101], v[32:33]
	v_mov_b64_e32 v[92:93], v[36:37]
	v_mov_b64_e32 v[96:97], v[40:41]
	v_mov_b64_e32 v[104:105], v[44:45]
	v_mov_b32_e32 v150, v128
	s_branch .LBB0_108

; DI void ln_phase(LAS unsigned char* lds, const Args& a, int l, int mode) {
;     ...
;         float s = 0.f;
; #pragma unroll
;         for (int i = 0; i < 4; ++i) s += (x[i][0] + x[i][1]) + (x[i][2] + x[i][3]);
;         const float mean = wave_sum(s) * (1.f / 1024.f);
;         float q = 0.f;
; #pragma unroll
;         for (int i = 0; i < 4; ++i) { x[i] = x[i] - mean; q += (x[i][0] * x[i][0] + x[i][1] * x[i][1]) + (x[i][2] * x[i][2] + x[i][3] * x[i][3]); }
;         const float rstd = rsqrtf(wave_sum(q) * (1.f / 1024.f) + 1e-5f);
.Lpart_done:
.LBB0_769:
	s_or_b64 exec, exec, s[36:37]
	v_mov_b32_e32 v82, v61
	v_mov_b32_e32 v83, v62
	v_mov_b32_e32 v92, v60
	v_mov_b32_e32 v93, v63
	v_pk_add_f32 v[82:83], v[82:83], v[92:93]
	v_mov_b32_e32 v92, v57
	v_mov_b32_e32 v93, v58
	v_mov_b32_e32 v94, v56
	v_mov_b32_e32 v95, v59
	v_pk_add_f32 v[92:93], v[92:93], v[94:95]
	v_add_f32_e32 v67, v82, v83
	v_pk_add_f32 v[92:93], v[92:93], v[92:93] op_sel_hi:[0,1]
	v_add_f32_e32 v83, 0, v67
	v_add_f32_e32 v95, v52, v53
	v_add_f32_e32 v97, v54, v55
	v_mov_b32_e32 v94, v48
	v_mov_b32_e32 v96, v49
	v_mov_b32_e32 v92, v50
	v_mov_b32_e32 v82, v51
	v_pk_add_f32 v[94:95], v[94:95], v[96:97]
	v_pk_add_f32 v[82:83], v[92:93], v[82:83]
	s_and_b64 s[18:19], exec, vcc
	v_pk_add_f32 v[82:83], v[94:95], v[82:83]
	s_or_b64 s[28:29], s[18:19], s[28:29]
	v_add_f32_e32 v67, v82, v83
	s_nop 1
	v_add_f32_dpp v67, v67, v67 quad_perm:[1,0,3,2] row_mask:0xf bank_mask:0xf
	s_nop 1
	v_add_f32_dpp v67, v67, v67 quad_perm:[2,3,0,1] row_mask:0xf bank_mask:0xf
	s_nop 1
	v_add_f32_dpp v67, v67, v67 row_half_mirror row_mask:0xf bank_mask:0xf
	s_nop 1
	v_add_f32_dpp v67, v67, v67 row_mirror row_mask:0xf bank_mask:0xf
	s_nop 0
	v_readlane_b32 s36, v67, 0
	v_readlane_b32 s37, v67, 16
	v_readlane_b32 s38, v67, 32
	v_readlane_b32 s39, v67, 48
	s_nop 1
	v_mov_b32_e32 v67, s36
	v_mov_b32_e32 v77, s38
	v_add_f32_e32 v67, s37, v67
	v_add_f32_e32 v77, s39, v77
	v_add_f32_e32 v67, v67, v77
	v_fmamk_f32 v61, v67, 0xba800000, v61
	v_fmamk_f32 v60, v67, 0xba800000, v60
	v_fmamk_f32 v63, v67, 0xba800000, v63
	v_fmamk_f32 v62, v67, 0xba800000, v62
	v_pk_mul_f32 v[82:83], v[62:63], v[62:63]
	v_pk_mul_f32 v[92:93], v[60:61], v[60:61]
	v_fmamk_f32 v57, v67, 0xba800000, v57
	v_pk_mov_b32 v[94:95], v[92:93], v[82:83] op_sel:[1,0]
	v_mov_b32_e32 v93, v83
	v_fmamk_f32 v56, v67, 0xba800000, v56
	v_fmamk_f32 v59, v67, 0xba800000, v59
	v_pk_add_f32 v[82:83], v[94:95], v[92:93]
	v_fmamk_f32 v58, v67, 0xba800000, v58
	v_pk_add_f32 v[82:83], v[82:83], v[82:83] op_sel_hi:[0,1]
	v_pk_mul_f32 v[92:93], v[58:59], v[58:59]
	v_pk_mul_f32 v[94:95], v[56:57], v[56:57]
	v_fmamk_f32 v52, v67, 0xba800000, v52
	v_pk_mov_b32 v[96:97], v[94:95], v[92:93] op_sel:[1,0]
	v_mov_b32_e32 v95, v93
	v_fmamk_f32 v53, v67, 0xba800000, v53
	v_fmamk_f32 v54, v67, 0xba800000, v54
	v_mul_f32_e32 v82, v52, v52
	v_pk_add_f32 v[92:93], v[96:97], v[94:95]
	v_fmamk_f32 v55, v67, 0xba800000, v55
	v_pk_fma_f32 v[94:95], v[52:53], v[52:53], v[82:83] op_sel_hi:[1,1,0]
	v_mul_f32_e32 v82, v54, v54
	v_pk_add_f32 v[92:93], v[92:93], v[92:93] op_sel_hi:[0,1]
	v_pk_fma_f32 v[96:97], v[54:55], v[54:55], v[82:83] op_sel_hi:[1,1,0]
	v_fmamk_f32 v51, v67, 0xba800000, v51
	v_fmamk_f32 v50, v67, 0xba800000, v50
	v_fmamk_f32 v49, v67, 0xba800000, v49
	v_fmac_f32_e32 v48, 0xba800000, v67
	v_mul_f32_e32 v94, v48, v48
	v_mul_f32_e32 v96, v49, v49
	v_mul_f32_e32 v82, v50, v50
	v_mul_f32_e32 v92, v51, v51
	v_pk_add_f32 v[94:95], v[94:95], v[96:97]
	v_pk_add_f32 v[82:83], v[82:83], v[92:93]
	s_nop 0
	v_pk_add_f32 v[82:83], v[94:95], v[82:83]
	s_nop 0
	v_add_f32_e32 v67, v82, v83
	s_nop 1
	v_add_f32_dpp v67, v67, v67 quad_perm:[1,0,3,2] row_mask:0xf bank_mask:0xf
	s_nop 1
	v_add_f32_dpp v67, v67, v67 quad_perm:[2,3,0,1] row_mask:0xf bank_mask:0xf
	s_nop 1
	v_add_f32_dpp v67, v67, v67 row_half_mirror row_mask:0xf bank_mask:0xf
	s_nop 1
	v_add_f32_dpp v67, v67, v67 row_mirror row_mask:0xf bank_mask:0xf
	s_nop 0
	v_readlane_b32 s36, v67, 0
	v_readlane_b32 s37, v67, 16
	v_readlane_b32 s38, v67, 32
	v_readlane_b32 s39, v67, 48
	s_nop 1
	v_mov_b32_e32 v67, s36
	v_mov_b32_e32 v77, s38
	v_add_f32_e32 v67, s37, v67
	v_add_f32_e32 v77, s39, v77
	v_add_f32_e32 v67, v67, v77
	v_fmamk_f32 v67, v67, 0x3a800000, v158
	v_mul_f32_e32 v77, 0x4b800000, v67
	v_cmp_gt_f32_e32 vcc, s46, v67
	s_nop 1
	v_cndmask_b32_e32 v67, v67, v77, vcc
	v_rsq_f32_e32 v67, v67
	s_nop 0
	v_mul_f32_e32 v77, 0x45800000, v67
	v_cndmask_b32_e32 v82, v67, v77, vcc
	v_pk_mul_f32 v[60:61], v[60:61], v[82:83] op_sel_hi:[1,0]
	v_pk_mul_f32 v[62:63], v[62:63], v[82:83] op_sel_hi:[1,0]
	v_pk_fma_f32 v[60:61], v[0:1], v[60:61], v[8:9]
	v_pk_fma_f32 v[62:63], v[2:3], v[62:63], v[10:11]
	v_pk_mul_f32 v[56:57], v[56:57], v[82:83] op_sel_hi:[1,0]
	v_pk_mul_f32 v[58:59], v[58:59], v[82:83] op_sel_hi:[1,0]
	v_cvt_pk_bf16_f32 v92, v60, v61
	v_cvt_pk_bf16_f32 v93, v62, v63
	v_pk_fma_f32 v[58:59], v[6:7], v[58:59], v[14:15]
	v_pk_fma_f32 v[56:57], v[4:5], v[56:57], v[12:13]
	v_pk_mul_f32 v[52:53], v[52:53], v[82:83] op_sel_hi:[1,0]
	v_pk_mul_f32 v[54:55], v[54:55], v[82:83] op_sel_hi:[1,0]
	v_pk_mul_f32 v[48:49], v[48:49], v[82:83] op_sel_hi:[1,0]
	v_pk_mul_f32 v[50:51], v[50:51], v[82:83] op_sel_hi:[1,0]
	global_store_dwordx2 v[80:81], v[92:93], off
	v_cvt_pk_bf16_f32 v92, v56, v57
	v_cvt_pk_bf16_f32 v93, v58, v59
	v_pk_fma_f32 v[54:55], v[18:19], v[54:55], v[26:27]
	v_pk_fma_f32 v[52:53], v[16:17], v[52:53], v[24:25]
	v_pk_fma_f32 v[50:51], v[22:23], v[50:51], v[30:31]
	v_pk_fma_f32 v[48:49], v[20:21], v[48:49], v[28:29]
	global_store_dwordx2 v[80:81], v[92:93], off offset:512
	v_cvt_pk_bf16_f32 v92, v52, v53
	v_cvt_pk_bf16_f32 v93, v54, v55
	v_cvt_pk_bf16_f32 v82, v48, v49
	v_cvt_pk_bf16_f32 v83, v50, v51
	s_andn2_b64 vcc, exec, s[34:35]
	global_store_dwordx2 v[80:81], v[92:93], off offset:1024
	global_store_dwordx2 v[80:81], v[82:83], off offset:1536
	s_cbranch_vccnz .LBB0_775
	v_cmp_lt_i32_e32 vcc, s57, v68
	s_mov_b64 s[18:19], 0
	s_and_saveexec_b64 s[36:37], vcc
	s_xor_b64 s[36:37], exec, s[36:37]
	s_cbranch_execnz .LBB0_779
	s_andn2_saveexec_b64 s[36:37], s[36:37]
	s_cbranch_execnz .LBB0_782

; #define LAS __attribute__((address_space(3)))
; DI void ln_phase(LAS unsigned char* lds, const Args& a, int l, int mode) {
;     ...
;         if (mode == 1) {
;             float d0 = 0.f, d1 = 0.f, d2 = 0.f, d3 = 0.f, d4 = 0.f, d5 = 0.f, d6 = 0.f, d7 = 0.f;
; #pragma unroll
;             for (int i = 0; i < 4; ++i) { const int ko = 256 * i + 4 * lane; f32x4 w;
;                 w = *(const LAS f32x4*)(w8s + 0 * 1024 + ko); d0 += (x[i][0] * w[0] + x[i][1] * w[1]) + (x[i][2] * w[2] + x[i][3] * w[3]);
;                 w = *(const LAS f32x4*)(w8s + 1 * 1024 + ko); d1 += (x[i][0] * w[0] + x[i][1] * w[1]) + (x[i][2] * w[2] + x[i][3] * w[3]);
;                 w = *(const LAS f32x4*)(w8s + 2 * 1024 + ko); d2 += (x[i][0] * w[0] + x[i][1] * w[1]) + (x[i][2] * w[2] + x[i][3] * w[3]);
;                 w = *(const LAS f32x4*)(w8s + 3 * 1024 + ko); d3 += (x[i][0] * w[0] + x[i][1] * w[1]) + (x[i][2] * w[2] + x[i][3] * w[3]);
;                 w = *(const LAS f32x4*)(w8s + 4 * 1024 + ko); d4 += (x[i][0] * w[0] + x[i][1] * w[1]) + (x[i][2] * w[2] + x[i][3] * w[3]);
;                 w = *(const LAS f32x4*)(w8s + 5 * 1024 + ko); d5 += (x[i][0] * w[0] + x[i][1] * w[1]) + (x[i][2] * w[2] + x[i][3] * w[3]);
;                 w = *(const LAS f32x4*)(w8s + 6 * 1024 + ko); d6 += (x[i][0] * w[0] + x[i][1] * w[1]) + (x[i][2] * w[2] + x[i][3] * w[3]);
;                 w = *(const LAS f32x4*)(w8s + 7 * 1024 + ko); d7 += (x[i][0] * w[0] + x[i][1] * w[1]) + (x[i][2] * w[2] + x[i][3] * w[3]); }
.LBB0_775:
	s_and_b64 vcc, exec, s[8:9]
	s_cbranch_vccnz .LBB0_763
	ds_read_b128 v[100:103], v91
	ds_read_b128 v[104:107], v91 offset:4096
	ds_read_b128 v[108:111], v91 offset:8192
	ds_read_b128 v[112:115], v91 offset:12288
	ds_read_b128 v[116:119], v91 offset:16384
	ds_read_b128 v[120:123], v91 offset:20480
	ds_read_b128 v[124:127], v91 offset:24576
	ds_read_b128 v[180:183], v91 offset:28672
	s_waitcnt lgkmcnt(7)
	v_mul_f32_e32 v67, v61, v101
	v_mul_f32_e32 v77, v63, v103
	v_fmac_f32_e32 v67, v60, v100
	v_fmac_f32_e32 v77, v62, v102
	v_add_f32_e32 v67, v67, v77
	v_add_f32_e32 v82, 0, v67
	s_waitcnt lgkmcnt(6)
	v_mul_f32_e32 v67, v61, v105
	v_mul_f32_e32 v77, v63, v107
	v_fmac_f32_e32 v67, v60, v104
	v_fmac_f32_e32 v77, v62, v106
	v_add_f32_e32 v67, v67, v77
	v_add_f32_e32 v83, 0, v67
	s_waitcnt lgkmcnt(5)
	v_mul_f32_e32 v67, v61, v109
	v_mul_f32_e32 v77, v63, v111
	v_fmac_f32_e32 v67, v60, v108
	v_fmac_f32_e32 v77, v62, v110
	v_add_f32_e32 v67, v67, v77
	v_add_f32_e32 v92, 0, v67
	s_waitcnt lgkmcnt(4)
	v_mul_f32_e32 v67, v61, v113
	v_mul_f32_e32 v77, v63, v115
	v_fmac_f32_e32 v67, v60, v112
	v_fmac_f32_e32 v77, v62, v114
	v_add_f32_e32 v67, v67, v77
	v_add_f32_e32 v93, 0, v67
	s_waitcnt lgkmcnt(3)
	v_mul_f32_e32 v67, v61, v117
	v_mul_f32_e32 v77, v63, v119
	v_fmac_f32_e32 v67, v60, v116
	v_fmac_f32_e32 v77, v62, v118
	v_add_f32_e32 v67, v67, v77
	v_add_f32_e32 v94, 0, v67
	s_waitcnt lgkmcnt(2)
	v_mul_f32_e32 v67, v61, v121
	v_mul_f32_e32 v77, v63, v123
	v_fmac_f32_e32 v67, v60, v120
	v_fmac_f32_e32 v77, v62, v122
	v_add_f32_e32 v67, v67, v77
	v_add_f32_e32 v77, 0, v67
	s_waitcnt lgkmcnt(1)
	v_mul_f32_e32 v67, v61, v125
	v_fmac_f32_e32 v67, v60, v124
	v_mul_f32_e32 v124, v63, v127
	v_fmac_f32_e32 v124, v62, v126
	v_add_f32_e32 v67, v67, v124
	v_add_f32_e32 v67, 0, v67
	s_waitcnt lgkmcnt(0)
	v_mul_f32_e32 v61, v61, v181
	v_fmac_f32_e32 v61, v60, v180
	v_mul_f32_e32 v60, v63, v183
	v_fmac_f32_e32 v60, v62, v182
	ds_read_b128 v[100:103], v91 offset:1024
	ds_read_b128 v[104:107], v91 offset:5120
	ds_read_b128 v[108:111], v91 offset:9216
	ds_read_b128 v[112:115], v91 offset:13312
	ds_read_b128 v[116:119], v91 offset:17408
	ds_read_b128 v[120:123], v91 offset:21504
	ds_read_b128 v[124:127], v91 offset:25600
	ds_read_b128 v[180:183], v91 offset:29696
	v_add_f32_e32 v60, v61, v60
	v_add_f32_e32 v60, 0, v60
	s_waitcnt lgkmcnt(7)
	v_mul_f32_e32 v61, v57, v101
	v_mul_f32_e32 v62, v59, v103
	v_fmac_f32_e32 v61, v56, v100
	v_fmac_f32_e32 v62, v58, v102
	v_add_f32_e32 v61, v61, v62
	v_add_f32_e32 v61, v82, v61
	s_waitcnt lgkmcnt(6)
	v_mul_f32_e32 v62, v57, v105
	v_mul_f32_e32 v63, v59, v107
	v_fmac_f32_e32 v62, v56, v104
	v_fmac_f32_e32 v63, v58, v106
	v_add_f32_e32 v62, v62, v63
	v_add_f32_e32 v62, v83, v62
	s_waitcnt lgkmcnt(5)
	v_mul_f32_e32 v63, v57, v109
	v_fmac_f32_e32 v63, v56, v108
	v_mul_f32_e32 v108, v59, v111
	v_fmac_f32_e32 v108, v58, v110
	v_add_f32_e32 v63, v63, v108
	v_add_f32_e32 v63, v92, v63
	s_waitcnt lgkmcnt(4)
	v_mul_f32_e32 v113, v57, v113
	v_fmac_f32_e32 v113, v56, v112
	v_mul_f32_e32 v112, v59, v115
	v_fmac_f32_e32 v112, v58, v114
	v_add_f32_e32 v112, v113, v112
	v_add_f32_e32 v82, v93, v112
	s_waitcnt lgkmcnt(3)
	v_mul_f32_e32 v117, v57, v117
	v_fmac_f32_e32 v117, v56, v116
	v_mul_f32_e32 v116, v59, v119
	v_fmac_f32_e32 v116, v58, v118
	v_add_f32_e32 v116, v117, v116
	v_add_f32_e32 v83, v94, v116
	s_waitcnt lgkmcnt(2)
	v_mul_f32_e32 v121, v57, v121
	v_fmac_f32_e32 v121, v56, v120
	v_mul_f32_e32 v120, v59, v123
	v_fmac_f32_e32 v120, v58, v122
	v_add_f32_e32 v120, v121, v120
	v_add_f32_e32 v77, v77, v120
	s_waitcnt lgkmcnt(1)
	v_mul_f32_e32 v125, v57, v125
	v_fmac_f32_e32 v125, v56, v124
	v_mul_f32_e32 v124, v59, v127
	v_fmac_f32_e32 v124, v58, v126
	v_add_f32_e32 v124, v125, v124
	v_add_f32_e32 v67, v67, v124
	s_waitcnt lgkmcnt(0)
	v_mul_f32_e32 v57, v57, v181
	v_fmac_f32_e32 v57, v56, v180
	v_mul_f32_e32 v56, v59, v183
	v_fmac_f32_e32 v56, v58, v182
	v_add_f32_e32 v56, v57, v56
	v_add_f32_e32 v60, v60, v56
	ds_read_b128 v[56:59], v91 offset:2048
	ds_read_b128 v[78:81], v91 offset:30720
	s_waitcnt lgkmcnt(1)
	v_mul_f32_e32 v57, v53, v57
	v_fmac_f32_e32 v57, v52, v56
	v_mul_f32_e32 v56, v55, v59
	v_fmac_f32_e32 v56, v54, v58
	v_add_f32_e32 v56, v57, v56
	v_add_f32_e32 v92, v61, v56
	ds_read_b128 v[56:59], v91 offset:6144
	s_waitcnt lgkmcnt(0)
	v_mul_f32_e32 v57, v53, v57
	v_fmac_f32_e32 v57, v52, v56
	v_mul_f32_e32 v56, v55, v59
	v_fmac_f32_e32 v56, v54, v58
	v_add_f32_e32 v56, v57, v56
	v_add_f32_e32 v62, v62, v56
	ds_read_b128 v[56:59], v91 offset:10240
	s_waitcnt lgkmcnt(0)
	v_mul_f32_e32 v57, v53, v57
	v_fmac_f32_e32 v57, v52, v56
	v_mul_f32_e32 v56, v55, v59
	v_fmac_f32_e32 v56, v54, v58
	v_add_f32_e32 v56, v57, v56
	v_add_f32_e32 v63, v63, v56
	ds_read_b128 v[56:59], v91 offset:14336
	s_waitcnt lgkmcnt(0)
	v_mul_f32_e32 v57, v53, v57
	v_fmac_f32_e32 v57, v52, v56
	v_mul_f32_e32 v56, v55, v59
	v_fmac_f32_e32 v56, v54, v58
	v_add_f32_e32 v56, v57, v56
	v_add_f32_e32 v82, v82, v56
	ds_read_b128 v[56:59], v91 offset:18432
	s_waitcnt lgkmcnt(0)
	v_mul_f32_e32 v57, v53, v57
	v_fmac_f32_e32 v57, v52, v56
	v_mul_f32_e32 v56, v55, v59
	v_fmac_f32_e32 v56, v54, v58
	v_add_f32_e32 v56, v57, v56
	v_add_f32_e32 v83, v83, v56
	ds_read_b128 v[56:59], v91 offset:22528
	s_waitcnt lgkmcnt(0)
	v_mul_f32_e32 v57, v53, v57
	v_fmac_f32_e32 v57, v52, v56
	v_mul_f32_e32 v56, v55, v59
	v_fmac_f32_e32 v56, v54, v58
	v_add_f32_e32 v56, v57, v56
	v_add_f32_e32 v61, v77, v56
	ds_read_b128 v[56:59], v91 offset:26624
	s_waitcnt lgkmcnt(0)
; #define LAS __attribute__((address_space(3)))
; DI void ln_phase(LAS unsigned char* lds, const Args& a, int l, int mode) {
;     ...
;                 w = *(const LAS f32x4*)(w8s + 0 * 1024 + ko); d0 += (x[i][0] * w[0] + x[i][1] * w[1]) + (x[i][2] * w[2] + x[i][3] * w[3]);
;                 w = *(const LAS f32x4*)(w8s + 1 * 1024 + ko); d1 += (x[i][0] * w[0] + x[i][1] * w[1]) + (x[i][2] * w[2] + x[i][3] * w[3]);
;                 w = *(const LAS f32x4*)(w8s + 2 * 1024 + ko); d2 += (x[i][0] * w[0] + x[i][1] * w[1]) + (x[i][2] * w[2] + x[i][3] * w[3]);
;                 w = *(const LAS f32x4*)(w8s + 3 * 1024 + ko); d3 += (x[i][0] * w[0] + x[i][1] * w[1]) + (x[i][2] * w[2] + x[i][3] * w[3]);
;                 w = *(const LAS f32x4*)(w8s + 4 * 1024 + ko); d4 += (x[i][0] * w[0] + x[i][1] * w[1]) + (x[i][2] * w[2] + x[i][3] * w[3]);
;                 w = *(const LAS f32x4*)(w8s + 5 * 1024 + ko); d5 += (x[i][0] * w[0] + x[i][1] * w[1]) + (x[i][2] * w[2] + x[i][3] * w[3]);
;                 w = *(const LAS f32x4*)(w8s + 6 * 1024 + ko); d6 += (x[i][0] * w[0] + x[i][1] * w[1]) + (x[i][2] * w[2] + x[i][3] * w[3]);
;                 w = *(const LAS f32x4*)(w8s + 7 * 1024 + ko); d7 += (x[i][0] * w[0] + x[i][1] * w[1]) + (x[i][2] * w[2] + x[i][3] * w[3]); }
;             d0 = wave_sum(d0); d1 = wave_sum(d1); d2 = wave_sum(d2); d3 = wave_sum(d3); d4 = wave_sum(d4); d5 = wave_sum(d5); d6 = wave_sum(d6); d7 = wave_sum(d7);
	v_mul_f32_e32 v57, v53, v57
	v_mul_f32_e32 v53, v53, v79
	v_fmac_f32_e32 v57, v52, v56
	v_fmac_f32_e32 v53, v52, v78
	v_mul_f32_e32 v52, v55, v81
	v_fmac_f32_e32 v52, v54, v80
	ds_read_b128 v[78:81], v91 offset:3072
	v_mul_f32_e32 v56, v55, v59
	v_fmac_f32_e32 v56, v54, v58
	v_add_f32_e32 v52, v53, v52
	v_add_f32_e32 v52, v60, v52
	s_waitcnt lgkmcnt(0)
	v_mul_f32_e32 v53, v49, v79
	v_mul_f32_e32 v54, v51, v81
	v_fmac_f32_e32 v53, v48, v78
	v_fmac_f32_e32 v54, v50, v80
	ds_read_b128 v[78:81], v91 offset:7168
	v_add_f32_e32 v53, v53, v54
	v_add_f32_e32 v60, v92, v53
	v_add_f32_e32 v56, v57, v56
	v_add_f32_e32 v56, v67, v56
	s_waitcnt lgkmcnt(0)
	v_mul_f32_e32 v53, v49, v79
	v_mul_f32_e32 v54, v51, v81
	v_fmac_f32_e32 v53, v48, v78
	v_fmac_f32_e32 v54, v50, v80
	ds_read_b128 v[78:81], v91 offset:11264
	v_add_f32_e32 v53, v53, v54
	v_add_f32_e32 v59, v62, v53
	s_waitcnt lgkmcnt(0)
	v_mul_f32_e32 v53, v49, v79
	v_mul_f32_e32 v54, v51, v81
	v_fmac_f32_e32 v53, v48, v78
	v_fmac_f32_e32 v54, v50, v80
	ds_read_b128 v[78:81], v91 offset:15360
	v_add_f32_e32 v53, v53, v54
	v_add_f32_e32 v57, v63, v53
	s_waitcnt lgkmcnt(0)
	v_mul_f32_e32 v53, v49, v79
	v_mul_f32_e32 v54, v51, v81
	v_fmac_f32_e32 v53, v48, v78
	v_fmac_f32_e32 v54, v50, v80
	ds_read_b128 v[78:81], v91 offset:19456
	v_add_f32_e32 v53, v53, v54
	v_add_f32_e32 v58, v82, v53
	s_waitcnt lgkmcnt(0)
	v_mul_f32_e32 v53, v49, v79
	v_mul_f32_e32 v54, v51, v81
	v_fmac_f32_e32 v53, v48, v78
	v_fmac_f32_e32 v54, v50, v80
	ds_read_b128 v[78:81], v91 offset:23552
	v_add_f32_e32 v53, v53, v54
	v_add_f32_e32 v55, v83, v53
	s_waitcnt lgkmcnt(0)
	v_mul_f32_e32 v53, v49, v79
	v_mul_f32_e32 v54, v51, v81
	v_fmac_f32_e32 v53, v48, v78
	v_fmac_f32_e32 v54, v50, v80
	ds_read_b128 v[78:81], v91 offset:27648
	v_add_f32_e32 v53, v53, v54
	v_add_f32_e32 v53, v61, v53
	s_waitcnt lgkmcnt(0)
	v_mul_f32_e32 v54, v49, v79
	v_mul_f32_e32 v61, v51, v81
	v_fmac_f32_e32 v54, v48, v78
	v_fmac_f32_e32 v61, v50, v80
	ds_read_b128 v[78:81], v91 offset:31744
	v_add_f32_e32 v54, v54, v61
	v_add_f32_e32 v54, v56, v54
	ds_bpermute_b32 v56, v85, v57
	ds_bpermute_b32 v61, v85, v53
	s_waitcnt lgkmcnt(2)
	v_mul_f32_e32 v49, v49, v79
	v_fmac_f32_e32 v49, v48, v78
	v_mul_f32_e32 v48, v51, v81
	v_fmac_f32_e32 v48, v50, v80
	v_add_f32_e32 v48, v49, v48
	v_add_f32_e32 v50, v52, v48
	ds_bpermute_b32 v48, v85, v60
	ds_bpermute_b32 v51, v85, v59
	ds_bpermute_b32 v62, v85, v54
	ds_bpermute_b32 v63, v85, v50
	s_waitcnt lgkmcnt(5)
	v_add_f32_e32 v56, v57, v56
	s_waitcnt lgkmcnt(3)
	v_add_f32_e32 v48, v60, v48
	s_waitcnt lgkmcnt(2)
	v_add_f32_e32 v51, v59, v51
	ds_bpermute_b32 v59, v85, v58
	ds_bpermute_b32 v60, v85, v55
	v_add_f32_e32 v53, v53, v61
	s_waitcnt lgkmcnt(3)
	v_add_f32_e32 v54, v54, v62
	s_waitcnt lgkmcnt(2)
	v_add_f32_e32 v50, v50, v63
	s_waitcnt lgkmcnt(1)
	v_add_f32_e32 v58, v58, v59
	s_waitcnt lgkmcnt(0)
	v_add_f32_e32 v55, v55, v60
	ds_bpermute_b32 v49, v86, v48
	ds_bpermute_b32 v52, v86, v51
	ds_bpermute_b32 v57, v86, v56
	ds_bpermute_b32 v59, v86, v58
	ds_bpermute_b32 v60, v86, v55
	ds_bpermute_b32 v61, v86, v53
	ds_bpermute_b32 v62, v86, v54
	ds_bpermute_b32 v63, v86, v50
	s_waitcnt lgkmcnt(7)
	v_add_f32_e32 v48, v48, v49
	s_waitcnt lgkmcnt(6)
	v_add_f32_e32 v51, v51, v52
	s_waitcnt lgkmcnt(5)
	v_add_f32_e32 v56, v56, v57
	s_waitcnt lgkmcnt(4)
	v_add_f32_e32 v58, v58, v59
	s_waitcnt lgkmcnt(3)
	v_add_f32_e32 v55, v55, v60
	s_waitcnt lgkmcnt(2)
	v_add_f32_e32 v53, v53, v61
	s_waitcnt lgkmcnt(1)
	v_add_f32_e32 v54, v54, v62
	s_waitcnt lgkmcnt(0)
	v_add_f32_e32 v50, v50, v63
	ds_bpermute_b32 v49, v87, v48
	ds_bpermute_b32 v52, v87, v51
	ds_bpermute_b32 v57, v87, v56
	ds_bpermute_b32 v59, v87, v58
	ds_bpermute_b32 v60, v87, v55
	ds_bpermute_b32 v61, v87, v53
	ds_bpermute_b32 v62, v87, v54
	ds_bpermute_b32 v63, v87, v50
	s_waitcnt lgkmcnt(7)
	v_add_f32_e32 v48, v48, v49
	s_waitcnt lgkmcnt(6)
	v_add_f32_e32 v51, v51, v52
	s_waitcnt lgkmcnt(5)
	v_add_f32_e32 v56, v56, v57
	s_waitcnt lgkmcnt(4)
	v_add_f32_e32 v58, v58, v59
	s_waitcnt lgkmcnt(3)
	v_add_f32_e32 v55, v55, v60
	s_waitcnt lgkmcnt(2)
	v_add_f32_e32 v53, v53, v61
	s_waitcnt lgkmcnt(1)
	v_add_f32_e32 v54, v54, v62
	s_waitcnt lgkmcnt(0)
	v_add_f32_e32 v50, v50, v63
	ds_bpermute_b32 v49, v88, v48
	ds_bpermute_b32 v52, v88, v51
	ds_bpermute_b32 v57, v88, v56
	ds_bpermute_b32 v59, v88, v58
	ds_bpermute_b32 v60, v88, v55
	ds_bpermute_b32 v61, v88, v53
	ds_bpermute_b32 v62, v88, v54
	ds_bpermute_b32 v63, v88, v50
	s_waitcnt lgkmcnt(7)
	v_add_f32_e32 v48, v48, v49
	s_waitcnt lgkmcnt(6)
	v_add_f32_e32 v51, v51, v52
	s_waitcnt lgkmcnt(5)
	v_add_f32_e32 v56, v56, v57
	s_waitcnt lgkmcnt(4)
	v_add_f32_e32 v58, v58, v59
	s_waitcnt lgkmcnt(3)
	v_add_f32_e32 v55, v55, v60
	s_waitcnt lgkmcnt(2)
	v_add_f32_e32 v53, v53, v61
	s_waitcnt lgkmcnt(1)
	v_add_f32_e32 v54, v54, v62
	s_waitcnt lgkmcnt(0)
	v_add_f32_e32 v50, v50, v63
	ds_bpermute_b32 v49, v89, v48
	ds_bpermute_b32 v52, v89, v51
	ds_bpermute_b32 v57, v89, v56
	ds_bpermute_b32 v59, v89, v58
	ds_bpermute_b32 v60, v89, v55
	ds_bpermute_b32 v61, v89, v53
	ds_bpermute_b32 v62, v89, v54
	ds_bpermute_b32 v63, v89, v50
	s_waitcnt lgkmcnt(7)
	v_add_f32_e32 v48, v48, v49
	s_waitcnt lgkmcnt(6)
	v_add_f32_e32 v51, v51, v52
	s_waitcnt lgkmcnt(5)
	v_add_f32_e32 v56, v56, v57
	s_waitcnt lgkmcnt(4)
	v_add_f32_e32 v58, v58, v59
	s_waitcnt lgkmcnt(3)
	v_add_f32_e32 v55, v55, v60
	s_waitcnt lgkmcnt(2)
	v_add_f32_e32 v53, v53, v61
	s_waitcnt lgkmcnt(1)
	v_add_f32_e32 v54, v54, v62
	s_waitcnt lgkmcnt(0)
	v_add_f32_e32 v50, v50, v63
	ds_bpermute_b32 v49, v90, v48
	ds_bpermute_b32 v52, v90, v51
	ds_bpermute_b32 v57, v90, v56
	ds_bpermute_b32 v59, v90, v58
	ds_bpermute_b32 v60, v90, v55
	ds_bpermute_b32 v61, v90, v53
	ds_bpermute_b32 v62, v90, v54
	ds_bpermute_b32 v63, v90, v50
	s_and_saveexec_b64 s[18:19], s[10:11]
	s_cbranch_execz .LBB0_762
; DI void ln_phase(LAS unsigned char* lds, const Args& a, int l, int mode) {
;     ...
;             if (lane < 4) { const float braw = lane == 0 ? d0 : (lane == 1 ? d1 : (lane == 2 ? d2 : d3)); const float araw = lane == 0 ? d4 : (lane == 1 ? d5 : (lane == 2 ? d6 : d7));
;                 const float xx = araw + dtb; const float sp = xx > 20.f ? xx : log1pf(expf(xx));
	s_waitcnt lgkmcnt(0)
	v_add_f32_e32 v50, v50, v63
	v_add_f32_e32 v54, v54, v62
	v_add_f32_e32 v53, v53, v61
	v_cndmask_b32_e64 v50, v50, v54, s[16:17]
	v_add_f32_e32 v55, v55, v60
	v_cndmask_b32_e64 v50, v50, v53, s[14:15]
	v_cndmask_b32_e64 v50, v50, v55, s[12:13]
	v_add_f32_e32 v50, v65, v50
	s_mov_b32 s25, 0x41a00000
	v_cmp_nlt_f32_e32 vcc, s25, v50
	s_and_saveexec_b64 s[36:37], vcc
	s_cbranch_execz .LBB0_761
	v_mul_f32_e32 v53, 0x3fb8aa3b, v50
	v_rndne_f32_e32 v54, v53
	s_mov_b32 s25, 0x3fb8aa3b
	v_sub_f32_e32 v55, v53, v54
	v_fma_f32 v53, v50, s25, -v53
	v_fmac_f32_e32 v53, 0x32a5705f, v50
	v_add_f32_e32 v53, v55, v53
	v_cvt_i32_f32_e32 v54, v54
	v_exp_f32_e32 v53, v53
	s_mov_b32 s25, 0xc2ce8ed0
	v_cmp_ngt_f32_e32 vcc, s25, v50
	s_mov_b32 s25, 0x42b17218
	v_ldexp_f32 v53, v53, v54
	v_cndmask_b32_e32 v53, 0, v53, vcc
	v_cmp_nlt_f32_e32 vcc, s25, v50
	s_mov_b32 s25, 0x3f2aaaab
	s_nop 0
	v_cndmask_b32_e32 v50, v165, v53, vcc
	v_add_f32_e32 v53, 1.0, v50
	v_add_f32_e32 v54, -1.0, v53
	v_sub_f32_e32 v55, v54, v53
	v_add_f32_e32 v55, 1.0, v55
	v_sub_f32_e32 v54, v50, v54
	v_add_f32_e32 v60, v54, v55
	v_frexp_mant_f32_e32 v61, v53
	v_cvt_f64_f32_e32 v[54:55], v53
	v_frexp_exp_i32_f64_e32 v54, v[54:55]
	v_cmp_gt_f32_e32 vcc, s25, v61
	s_mov_b32 s25, 0x3f317218
	s_nop 0
	v_subbrev_co_u32_e32 v67, vcc, 0, v54, vcc
	v_sub_u32_e32 v54, 0, v67
	v_ldexp_f32 v53, v53, v54
	v_ldexp_f32 v54, v60, v54
	v_add_f32_e32 v60, -1.0, v53
	v_add_f32_e32 v55, 1.0, v60
	v_sub_f32_e32 v55, v53, v55
	v_add_f32_e32 v61, v54, v55
	v_add_f32_e32 v55, 1.0, v53
	v_add_f32_e32 v62, -1.0, v55
	v_sub_f32_e32 v53, v53, v62
	v_add_f32_e32 v53, v54, v53
	v_add_f32_e32 v77, v55, v53
	v_rcp_f32_e32 v80, v77
	v_sub_f32_e32 v54, v55, v77
	v_add_f32_e32 v55, v60, v61
	v_add_f32_e32 v53, v53, v54
	v_mul_f32_e32 v82, v55, v80
	v_sub_f32_e32 v54, v60, v55
	v_mul_f32_e32 v60, v77, v82
	v_fma_f32 v62, v82, v77, -v60
	v_fmac_f32_e32 v62, v82, v53
	v_add_f32_e32 v81, v61, v54
	v_add_f32_e32 v54, v60, v62
	v_sub_f32_e32 v61, v55, v54
	v_pk_add_f32 v[78:79], v[54:55], v[60:61] neg_lo:[0,1] neg_hi:[0,1]
	v_mov_b32_e32 v63, v54
	v_pk_add_f32 v[54:55], v[78:79], v[62:63] neg_lo:[0,1] neg_hi:[0,1]
	s_nop 0
	v_add_f32_e32 v55, v81, v55
	v_add_f32_e32 v54, v54, v55
	v_add_f32_e32 v55, v61, v54
	v_mul_f32_e32 v81, v80, v55
	v_mul_f32_e32 v60, v77, v81
	v_fma_f32 v62, v81, v77, -v60
	v_fmac_f32_e32 v62, v81, v53
	v_sub_f32_e32 v53, v61, v55
	v_add_f32_e32 v53, v54, v53
	v_add_f32_e32 v54, v60, v62
	v_sub_f32_e32 v61, v55, v54
	v_pk_add_f32 v[78:79], v[54:55], v[60:61] neg_lo:[0,1] neg_hi:[0,1]
	v_mov_b32_e32 v63, v54
	v_pk_add_f32 v[54:55], v[78:79], v[62:63] neg_lo:[0,1] neg_hi:[0,1]
	s_nop 0
	v_add_f32_e32 v53, v53, v55
	v_add_f32_e32 v53, v54, v53
	v_add_f32_e32 v55, v82, v81
	v_add_f32_e32 v53, v61, v53
	v_sub_f32_e32 v54, v55, v82
	v_mul_f32_e32 v53, v80, v53
	v_sub_f32_e32 v54, v81, v54
	v_add_f32_e32 v53, v54, v53
	v_add_f32_e32 v60, v55, v53
	v_mul_f32_e32 v62, v60, v60
	v_fmamk_f32 v54, v62, 0x3e9b6dac, v159
	v_fmaak_f32 v131, v62, v54, 0x3f2aaada
	v_cvt_f32_i32_e32 v54, v67
	v_sub_f32_e32 v55, v60, v55
	v_sub_f32_e32 v53, v53, v55
	v_mul_f32_e32 v55, v60, v62
	v_pk_mul_f32 v[62:63], v[54:55], v[130:131]
	v_ldexp_f32 v61, v60, 1
	v_fma_f32 v60, v54, s25, -v62
	v_fmac_f32_e32 v60, 0xb102e308, v54
	v_pk_add_f32 v[54:55], v[62:63], v[60:61]
	v_ldexp_f32 v53, v53, 1
	v_sub_f32_e32 v61, v55, v61
	v_sub_f32_e32 v61, v63, v61
	v_add_f32_e32 v79, v53, v61
	v_mov_b32_e32 v78, v62
	v_pk_add_f32 v[62:63], v[54:55], v[62:63] neg_lo:[0,1] neg_hi:[0,1]
	v_pk_add_f32 v[80:81], v[54:55], v[78:79]
	v_mov_b32_e32 v61, v54
	v_mov_b32_e32 v63, v81
	v_pk_add_f32 v[82:83], v[60:61], v[62:63] neg_lo:[0,1] neg_hi:[0,1]
	v_pk_add_f32 v[60:61], v[60:61], v[62:63]
	v_mov_b32_e32 v78, v79
	v_pk_add_f32 v[62:63], v[60:61], v[54:55] op_sel:[1,0] op_sel_hi:[0,1] neg_lo:[0,1] neg_hi:[0,1]
	v_pk_add_f32 v[92:93], v[80:81], v[62:63] op_sel_hi:[1,0] neg_lo:[0,1] neg_hi:[0,1]
	v_mov_b32_e32 v80, v81
	v_mov_b32_e32 v81, v61
	v_pk_mov_b32 v[62:63], v[54:55], v[62:63] op_sel:[1,0]
	v_mov_b32_e32 v79, v54
	v_pk_add_f32 v[62:63], v[80:81], v[62:63] neg_lo:[0,1] neg_hi:[0,1]
	v_mov_b32_e32 v92, v82
	v_pk_add_f32 v[54:55], v[78:79], v[62:63] neg_lo:[0,1] neg_hi:[0,1]
	v_mov_b32_e32 v83, v61
	v_pk_add_f32 v[62:63], v[92:93], v[54:55]
	s_mov_b32 s25, 0x7f800000
	v_pk_add_f32 v[78:79], v[62:63], v[62:63] op_sel:[0,1] op_sel_hi:[1,0]
	v_cmp_neq_f32_e32 vcc, s25, v50
	v_pk_add_f32 v[60:61], v[60:61], v[78:79] op_sel:[1,0] op_sel_hi:[0,1]
	v_mov_b32_e32 v63, v60
	v_pk_add_f32 v[80:81], v[62:63], v[82:83] neg_lo:[0,1] neg_hi:[0,1]
	v_mov_b32_e32 v55, v78
	v_sub_f32_e32 v53, v62, v80
	v_pk_add_f32 v[54:55], v[54:55], v[80:81] neg_lo:[0,1] neg_hi:[0,1]
	v_sub_f32_e32 v53, v82, v53
	v_add_f32_e32 v53, v54, v53
	v_add_f32_e32 v53, v53, v55
	v_add_f32_e32 v53, v60, v53
	s_mov_b32 s25, 0x33800000
	v_cndmask_b32_e32 v53, v165, v53, vcc
	v_cmp_lt_f32_e64 vcc, |v50|, s25
	s_nop 1
	v_cndmask_b32_e32 v50, v53, v50, vcc
	s_branch .LBB0_761
